# attention: rpb table staged to LDS only when the head index changes (once per workgroup) instead of a load+wait every round
# baseline (speedup 1.0000x reference)
.LBB0_444:
	s_or_b64 exec, exec, s[12:13]
	s_lshr_b32 s2, s2, 6
	s_add_u32 s3, s80, 0x14000000
	s_addc_u32 s30, s81, 0
	s_ashr_i32 s11, s10, 31
	s_add_i32 s12, s2, s17
	s_lshl_b64 s[10:11], s[10:11], 12
	s_lshl_b32 s12, s12, 6
	s_add_u32 s10, s10, s12
	s_addc_u32 s11, s11, 0
	s_or_b32 s10, s10, s15
	s_lshl_b64 s[10:11], s[10:11], 10
	s_add_u32 s10, s3, s10
	s_addc_u32 s11, s30, s11
	s_lshl_b32 s13, s16, 7
	s_add_u32 s10, s10, s13
	s_addc_u32 s11, s11, 0
	v_and_b32_e32 v173, 15, v0
	v_mov_b32_e32 v127, 0
	s_add_u32 s8, s8, s12
	v_bfe_u32 v91, v0, 4, 2
	v_lshlrev_b32_e32 v70, 10, v173
	v_mov_b32_e32 v71, v127
	s_addc_u32 s9, s9, 0
	s_or_b32 s8, s8, s15
	v_lshl_add_u64 v[72:73], s[10:11], 0, v[70:71]
	v_lshlrev_b32_e32 v142, 3, v91
	v_mov_b32_e32 v143, v127
	s_lshl_b64 s[8:9], s[8:9], 7
	v_lshl_add_u64 v[72:73], v[72:73], 0, v[142:143]
	s_add_u32 s8, s24, s8
	global_load_dwordx2 v[146:147], v[72:73], off offset:96
	global_load_dwordx2 v[158:159], v[72:73], off offset:64
	global_load_dwordx2 v[160:161], v[72:73], off offset:32
	global_load_dwordx2 v[162:163], v[72:73], off
	s_addc_u32 s9, s25, s9
	v_lshlrev_b32_e32 v72, 7, v173
	v_mov_b32_e32 v73, v127
	v_lshl_add_u64 v[74:75], s[8:9], 0, v[72:73]
	v_lshlrev_b32_e32 v88, 4, v91
	v_mov_b32_e32 v89, v127
	v_lshl_add_u64 v[78:79], v[74:75], 0, v[88:89]
	global_load_dwordx4 v[74:77], v[78:79], off offset:64
	s_nop 0
	global_load_dwordx4 v[78:81], v[78:79], off
	v_lshrrev_b32_e32 v96, 5, v0
	v_and_b32_e32 v94, 7, v0
	v_bfe_u32 v95, v0, 4, 1
	v_and_b32_e32 v96, 6, v96
	v_bitop3_b32 v94, v95, v94, v96 bitop3:0x36
	v_and_b32_e32 v67, 0xf80, v69
	v_lshlrev_b32_e32 v94, 4, v94
	v_add3_u32 v143, 0, v67, v94
	v_bitop3_b32 v67, v69, 48, v0 bitop3:0x48
	v_add3_u32 v174, 0, v85, v67
	v_mov_b32_e32 v67, v127
	v_lshl_add_u64 v[66:67], s[0:1], 0, v[66:67]
	v_mov_b32_e32 v69, v127
	v_lshl_add_u64 v[148:149], v[66:67], 0, v[68:69]
	v_lshl_add_u64 v[66:67], s[24:25], 0, v[72:73]
	v_lshrrev_b32_e32 v71, 4, v0
	v_lshl_add_u64 v[150:151], v[66:67], 0, v[88:89]
	v_bfe_u32 v66, v0, 1, 3
	v_bitop3_b32 v67, v71, v66, 3 bitop3:0x6c
	v_bitop3_b32 v66, v91, v66, 4 bitop3:0x36
	v_lshlrev_b32_e32 v178, 4, v66
	v_mbcnt_lo_u32_b32 v66, -1, 0
	v_mbcnt_hi_u32_b32 v66, -1, v66
	v_and_b32_e32 v68, 64, v66
	v_lshlrev_b32_e32 v177, 4, v67
	v_xor_b32_e32 v67, 16, v66
	v_add_u32_e32 v68, 64, v68
	v_cmp_lt_i32_e32 vcc, v67, v68
	v_lshlrev_b32_e32 v93, 6, v173
	v_lshlrev_b32_e32 v92, 1, v0
	v_cndmask_b32_e32 v67, v66, v67, vcc
	v_lshlrev_b32_e32 v179, 2, v67
	v_xor_b32_e32 v67, 32, v66
	v_cmp_lt_i32_e32 vcc, v67, v68
	v_lshlrev_b32_e32 v90, 9, v173
	s_movk_i32 s8, 0x1d1
	v_cndmask_b32_e32 v66, v66, v67, vcc
	v_lshlrev_b32_e32 v180, 2, v66
	v_xor_b32_e32 v66, v71, v82
	v_lshlrev_b32_e32 v66, 4, v66
	v_and_b32_e32 v66, 48, v66
	v_add3_u32 v181, 0, v93, v66
	v_lshlrev_b32_e32 v66, 4, v87
	s_add_i32 s10, 0, 0x1e100
	v_and_b32_e32 v152, 0xf000, v66
	v_and_or_b32 v66, v92, 24, v83
	v_lshlrev_b32_e32 v144, 2, v91
	v_add_u32_e32 v175, 0xf000, v174
	v_cmp_gt_u32_e64 s[8:9], s8, v0
	v_lshl_add_u32 v176, v0, 2, s10
	v_lshl_add_u32 v182, v66, 7, 0
	s_lshl_b32 s31, s82, 1
	v_add_u32_e32 v183, v174, v84
	v_add_u32_e32 v184, v174, v86
	v_lshlrev_b32_e32 v154, 1, v90
	s_mov_b32 s33, 0xff800000
	v_lshlrev_b32_e32 v156, 1, v70
	v_mov_b32_e32 v185, 0x358637bd
	s_mov_b32 s34, 0x800000
	v_mov_b32_e32 v186, 0xff800000
	s_mov_b32 s48, -1
	s_mov_b32 s15, s86
	s_branch .LBB0_447

.LBB0_450:
	s_cmp_eq_u32 s37, s48
	s_cbranch_scc1 .LBB0_451
	s_mov_b32 s48, s37
	s_mul_i32 s10, s37, 0x1d1
	v_add_lshl_u32 v66, s10, v0, 2
	global_load_dword v66, v66, s[68:69]
	s_waitcnt vmcnt(0)
	v_mul_f32_e32 v66, 0x3fb8aa3b, v66
	ds_write_b32 v176, v66
